# packed f32 mul/add (v_pk_mul_f32, v_pk_add_f32) in the in-proj gate-tile sigmoid epilogue instead of scalar pairs
# baseline (speedup 1.0000x reference)
.LBB0_244:
	v_mov_b32_e32 v242, 0xbfb8aa3b
	v_mov_b32_e32 v243, 0xbfb8aa3b
	v_mov_b32_e32 v244, 1.0
	v_mov_b32_e32 v245, 1.0
	s_lshl_b32 s9, s35, 3
	s_lshl_b32 s7, s36, 7
	s_add_i32 s9, s30, s9
	s_add_i32 s14, s9, s7
	s_ashr_i32 s15, s14, 31
	s_lshl_b64 s[14:15], s[14:15], 14
	v_lshl_add_u64 v[156:157], v[138:139], 0, s[14:15]
	v_pk_mul_f32 v[96:97], v[96:97], v[242:243]
	v_exp_f32_e32 v96, v96
	v_exp_f32_e32 v97, v97
	s_nop 0
	v_pk_add_f32 v[96:97], v[96:97], v[244:245]
	v_rcp_f32_e32 v96, v96
	v_rcp_f32_e32 v97, v97
	s_nop 0
	v_cvt_pk_bf16_f32 v97, v96, v97
	v_pk_mul_f32 v[94:95], v[94:95], v[242:243]
	v_exp_f32_e32 v94, v94
	v_exp_f32_e32 v95, v95
	s_nop 0
	v_pk_add_f32 v[94:95], v[94:95], v[244:245]
	v_rcp_f32_e32 v94, v94
	v_rcp_f32_e32 v95, v95
	s_nop 0
	v_cvt_pk_bf16_f32 v96, v94, v95
	v_pk_mul_f32 v[90:91], v[90:91], v[242:243]
	v_exp_f32_e32 v90, v90
	v_exp_f32_e32 v91, v91
	s_nop 0
	v_pk_add_f32 v[90:91], v[90:91], v[244:245]
	v_rcp_f32_e32 v90, v90
	v_rcp_f32_e32 v91, v91
	s_nop 0
	v_cvt_pk_bf16_f32 v94, v90, v91
	v_add_co_u32_e32 v90, vcc, s63, v156
	s_movk_i32 s7, 0x2000
	s_nop 0
	v_addc_co_u32_e32 v91, vcc, 0, v157, vcc
	v_pk_mul_f32 v[92:93], v[92:93], v[242:243]
	v_exp_f32_e32 v92, v92
	v_exp_f32_e32 v93, v93
	s_nop 0
	v_pk_add_f32 v[92:93], v[92:93], v[244:245]
	v_rcp_f32_e32 v92, v92
	v_rcp_f32_e32 v93, v93
	s_nop 0
	v_cvt_pk_bf16_f32 v95, v92, v93
	v_add_co_u32_e32 v92, vcc, s7, v156
	s_movk_i32 s7, 0x3000
	s_nop 0
	v_addc_co_u32_e32 v93, vcc, 0, v157, vcc
	v_pk_mul_f32 v[32:33], v[32:33], v[242:243]
	v_exp_f32_e32 v32, v32
	v_exp_f32_e32 v33, v33
	s_nop 0
	v_pk_add_f32 v[32:33], v[32:33], v[244:245]
	v_rcp_f32_e32 v32, v32
	v_rcp_f32_e32 v33, v33
	s_nop 0
	v_cvt_pk_bf16_f32 v33, v32, v33
	v_pk_mul_f32 v[30:31], v[30:31], v[242:243]
	v_exp_f32_e32 v30, v30
	v_exp_f32_e32 v31, v31
	s_nop 0
	v_pk_add_f32 v[30:31], v[30:31], v[244:245]
	v_rcp_f32_e32 v30, v30
	v_rcp_f32_e32 v31, v31
	s_nop 0
	v_cvt_pk_bf16_f32 v32, v30, v31
	v_pk_mul_f32 v[26:27], v[26:27], v[242:243]
	v_exp_f32_e32 v26, v26
	v_exp_f32_e32 v27, v27
	s_nop 0
	v_pk_add_f32 v[26:27], v[26:27], v[244:245]
	v_rcp_f32_e32 v26, v26
	v_rcp_f32_e32 v27, v27
	s_nop 0
	v_cvt_pk_bf16_f32 v30, v26, v27
	v_add_co_u32_e32 v26, vcc, s7, v156
	v_pk_mul_f32 v[128:129], v[128:129], v[242:243]
	v_exp_f32_e32 v128, v128
	v_exp_f32_e32 v129, v129
	s_nop 0
	v_pk_add_f32 v[128:129], v[128:129], v[244:245]
	v_rcp_f32_e32 v128, v128
	v_rcp_f32_e32 v129, v129
	s_nop 0
	v_cvt_pk_bf16_f32 v129, v128, v129
	v_pk_mul_f32 v[126:127], v[126:127], v[242:243]
	v_exp_f32_e32 v126, v126
	v_exp_f32_e32 v127, v127
	s_nop 0
	v_pk_add_f32 v[126:127], v[126:127], v[244:245]
	v_rcp_f32_e32 v126, v126
	v_rcp_f32_e32 v127, v127
	s_nop 0
	v_cvt_pk_bf16_f32 v128, v126, v127
	v_pk_mul_f32 v[124:125], v[124:125], v[242:243]
	v_exp_f32_e32 v124, v124
	v_exp_f32_e32 v125, v125
	s_nop 0
	v_pk_add_f32 v[124:125], v[124:125], v[244:245]
	v_rcp_f32_e32 v124, v124
	v_rcp_f32_e32 v125, v125
	s_nop 0
	v_cvt_pk_bf16_f32 v127, v124, v125
	v_pk_mul_f32 v[122:123], v[122:123], v[242:243]
	v_exp_f32_e32 v122, v122
	v_exp_f32_e32 v123, v123
	s_nop 0
	v_pk_add_f32 v[122:123], v[122:123], v[244:245]
	v_rcp_f32_e32 v122, v122
	v_rcp_f32_e32 v123, v123
	s_nop 0
	v_cvt_pk_bf16_f32 v126, v122, v123
	global_store_dwordx4 v[156:157], v[126:129], off
	v_pk_mul_f32 v[120:121], v[120:121], v[242:243]
	v_exp_f32_e32 v120, v120
	v_exp_f32_e32 v121, v121
	s_nop 0
	v_pk_add_f32 v[120:121], v[120:121], v[244:245]
	v_rcp_f32_e32 v120, v120
	v_rcp_f32_e32 v121, v121
	s_nop 0
	v_cvt_pk_bf16_f32 v121, v120, v121
	v_pk_mul_f32 v[118:119], v[118:119], v[242:243]
	v_exp_f32_e32 v118, v118
	v_exp_f32_e32 v119, v119
	s_nop 0
	v_pk_add_f32 v[118:119], v[118:119], v[244:245]
	v_rcp_f32_e32 v118, v118
	v_rcp_f32_e32 v119, v119
	s_nop 0
	v_cvt_pk_bf16_f32 v120, v118, v119
	v_pk_mul_f32 v[116:117], v[116:117], v[242:243]
	v_exp_f32_e32 v116, v116
	v_exp_f32_e32 v117, v117
	s_nop 0
	v_pk_add_f32 v[116:117], v[116:117], v[244:245]
	v_rcp_f32_e32 v116, v116
	v_rcp_f32_e32 v117, v117
	s_nop 0
	v_cvt_pk_bf16_f32 v119, v116, v117
	v_pk_mul_f32 v[114:115], v[114:115], v[242:243]
	v_exp_f32_e32 v114, v114
	v_exp_f32_e32 v115, v115
	s_nop 0
	v_pk_add_f32 v[114:115], v[114:115], v[244:245]
	v_rcp_f32_e32 v114, v114
	v_rcp_f32_e32 v115, v115
	s_nop 0
	v_cvt_pk_bf16_f32 v118, v114, v115
	global_store_dwordx4 v[156:157], v[118:121], off offset:1024
	v_pk_mul_f32 v[112:113], v[112:113], v[242:243]
	v_exp_f32_e32 v112, v112
	v_exp_f32_e32 v113, v113
	s_nop 0
	v_pk_add_f32 v[112:113], v[112:113], v[244:245]
	v_rcp_f32_e32 v112, v112
	v_rcp_f32_e32 v113, v113
	s_nop 0
	v_cvt_pk_bf16_f32 v113, v112, v113
	v_pk_mul_f32 v[110:111], v[110:111], v[242:243]
	v_exp_f32_e32 v110, v110
	v_exp_f32_e32 v111, v111
	s_nop 0
	v_pk_add_f32 v[110:111], v[110:111], v[244:245]
	v_rcp_f32_e32 v110, v110
	v_rcp_f32_e32 v111, v111
	s_nop 0
	v_cvt_pk_bf16_f32 v112, v110, v111
	v_pk_mul_f32 v[108:109], v[108:109], v[242:243]
	v_exp_f32_e32 v108, v108
	v_exp_f32_e32 v109, v109
	s_nop 0
	v_pk_add_f32 v[108:109], v[108:109], v[244:245]
	v_rcp_f32_e32 v108, v108
	v_rcp_f32_e32 v109, v109
	s_nop 0
	v_cvt_pk_bf16_f32 v111, v108, v109
	v_pk_mul_f32 v[106:107], v[106:107], v[242:243]
	v_exp_f32_e32 v106, v106
	v_exp_f32_e32 v107, v107
	s_nop 0
	v_pk_add_f32 v[106:107], v[106:107], v[244:245]
	v_rcp_f32_e32 v106, v106
	v_rcp_f32_e32 v107, v107
	s_nop 0
	v_cvt_pk_bf16_f32 v110, v106, v107
	global_store_dwordx4 v[156:157], v[110:113], off offset:2048
	v_pk_mul_f32 v[104:105], v[104:105], v[242:243]
	v_exp_f32_e32 v104, v104
	v_exp_f32_e32 v105, v105
	s_nop 0
	v_pk_add_f32 v[104:105], v[104:105], v[244:245]
	v_rcp_f32_e32 v104, v104
	v_rcp_f32_e32 v105, v105
	s_nop 0
	v_cvt_pk_bf16_f32 v105, v104, v105
	v_pk_mul_f32 v[102:103], v[102:103], v[242:243]
	v_exp_f32_e32 v102, v102
	v_exp_f32_e32 v103, v103
	s_nop 0
	v_pk_add_f32 v[102:103], v[102:103], v[244:245]
	v_rcp_f32_e32 v102, v102
	v_rcp_f32_e32 v103, v103
	s_nop 0
	v_cvt_pk_bf16_f32 v104, v102, v103
	v_pk_mul_f32 v[100:101], v[100:101], v[242:243]
	v_exp_f32_e32 v100, v100
	v_exp_f32_e32 v101, v101
	s_nop 0
	v_pk_add_f32 v[100:101], v[100:101], v[244:245]
	v_rcp_f32_e32 v100, v100
	v_rcp_f32_e32 v101, v101
	s_nop 0
	v_cvt_pk_bf16_f32 v103, v100, v101
	v_pk_mul_f32 v[98:99], v[98:99], v[242:243]
	v_exp_f32_e32 v98, v98
	v_exp_f32_e32 v99, v99
	s_nop 0
	v_pk_add_f32 v[98:99], v[98:99], v[244:245]
	v_rcp_f32_e32 v98, v98
	v_rcp_f32_e32 v99, v99
	s_nop 0
	v_cvt_pk_bf16_f32 v102, v98, v99
	global_store_dwordx4 v[156:157], v[102:105], off offset:3072
	global_store_dwordx4 v[92:93], v[94:97], off offset:-4096
	v_pk_mul_f32 v[88:89], v[88:89], v[242:243]
	v_exp_f32_e32 v88, v88
	v_exp_f32_e32 v89, v89
	s_nop 0
	v_pk_add_f32 v[88:89], v[88:89], v[244:245]
	v_rcp_f32_e32 v88, v88
	v_rcp_f32_e32 v89, v89
	s_nop 0
	v_cvt_pk_bf16_f32 v89, v88, v89
	v_pk_mul_f32 v[86:87], v[86:87], v[242:243]
	v_exp_f32_e32 v86, v86
	v_exp_f32_e32 v87, v87
	s_nop 0
	v_pk_add_f32 v[86:87], v[86:87], v[244:245]
	v_rcp_f32_e32 v86, v86
	v_rcp_f32_e32 v87, v87
	s_nop 0
	v_cvt_pk_bf16_f32 v88, v86, v87
	v_pk_mul_f32 v[84:85], v[84:85], v[242:243]
	v_exp_f32_e32 v84, v84
	v_exp_f32_e32 v85, v85
	s_nop 0
	v_pk_add_f32 v[84:85], v[84:85], v[244:245]
	v_rcp_f32_e32 v84, v84
	v_rcp_f32_e32 v85, v85
	s_nop 0
	v_cvt_pk_bf16_f32 v87, v84, v85
	v_pk_mul_f32 v[82:83], v[82:83], v[242:243]
	v_exp_f32_e32 v82, v82
	v_exp_f32_e32 v83, v83
	s_nop 0
	v_pk_add_f32 v[82:83], v[82:83], v[244:245]
	v_rcp_f32_e32 v82, v82
	v_rcp_f32_e32 v83, v83
	s_nop 0
	v_cvt_pk_bf16_f32 v86, v82, v83
	global_store_dwordx4 v[90:91], v[86:89], off offset:1024
	v_pk_mul_f32 v[80:81], v[80:81], v[242:243]
	v_exp_f32_e32 v80, v80
	v_exp_f32_e32 v81, v81
	s_nop 0
	v_pk_add_f32 v[80:81], v[80:81], v[244:245]
	v_rcp_f32_e32 v80, v80
	v_rcp_f32_e32 v81, v81
	s_nop 0
	v_cvt_pk_bf16_f32 v81, v80, v81
	v_pk_mul_f32 v[78:79], v[78:79], v[242:243]
	v_exp_f32_e32 v78, v78
	v_exp_f32_e32 v79, v79
	s_nop 0
	v_pk_add_f32 v[78:79], v[78:79], v[244:245]
	v_rcp_f32_e32 v78, v78
	v_rcp_f32_e32 v79, v79
	s_nop 0
	v_cvt_pk_bf16_f32 v80, v78, v79
	v_pk_mul_f32 v[76:77], v[76:77], v[242:243]
	v_exp_f32_e32 v76, v76
	v_exp_f32_e32 v77, v77
	s_nop 0
	v_pk_add_f32 v[76:77], v[76:77], v[244:245]
	v_rcp_f32_e32 v76, v76
	v_rcp_f32_e32 v77, v77
	s_nop 0
	v_cvt_pk_bf16_f32 v79, v76, v77
	v_pk_mul_f32 v[74:75], v[74:75], v[242:243]
	v_exp_f32_e32 v74, v74
	v_exp_f32_e32 v75, v75
	s_nop 0
	v_pk_add_f32 v[74:75], v[74:75], v[244:245]
	v_rcp_f32_e32 v74, v74
	v_rcp_f32_e32 v75, v75
	s_nop 0
	v_cvt_pk_bf16_f32 v78, v74, v75
	global_store_dwordx4 v[90:91], v[78:81], off offset:2048
	v_pk_mul_f32 v[72:73], v[72:73], v[242:243]
	v_exp_f32_e32 v72, v72
	v_exp_f32_e32 v73, v73
	s_nop 0
	v_pk_add_f32 v[72:73], v[72:73], v[244:245]
	v_rcp_f32_e32 v72, v72
	v_rcp_f32_e32 v73, v73
	s_nop 0
	v_cvt_pk_bf16_f32 v73, v72, v73
	v_pk_mul_f32 v[70:71], v[70:71], v[242:243]
	v_exp_f32_e32 v70, v70
	v_exp_f32_e32 v71, v71
	s_nop 0
	v_pk_add_f32 v[70:71], v[70:71], v[244:245]
	v_rcp_f32_e32 v70, v70
	v_rcp_f32_e32 v71, v71
	s_nop 0
	v_cvt_pk_bf16_f32 v72, v70, v71
	v_pk_mul_f32 v[68:69], v[68:69], v[242:243]
	v_exp_f32_e32 v68, v68
	v_exp_f32_e32 v69, v69
	s_nop 0
	v_pk_add_f32 v[68:69], v[68:69], v[244:245]
	v_rcp_f32_e32 v68, v68
	v_rcp_f32_e32 v69, v69
	s_nop 0
	v_cvt_pk_bf16_f32 v71, v68, v69
	v_pk_mul_f32 v[66:67], v[66:67], v[242:243]
	v_exp_f32_e32 v66, v66
	v_exp_f32_e32 v67, v67
	s_nop 0
	v_pk_add_f32 v[66:67], v[66:67], v[244:245]
	v_rcp_f32_e32 v66, v66
	v_rcp_f32_e32 v67, v67
	s_nop 0
	v_cvt_pk_bf16_f32 v70, v66, v67
	global_store_dwordx4 v[90:91], v[70:73], off offset:3072
	v_pk_mul_f32 v[64:65], v[64:65], v[242:243]
	v_exp_f32_e32 v64, v64
	v_exp_f32_e32 v65, v65
	s_nop 0
	v_pk_add_f32 v[64:65], v[64:65], v[244:245]
	v_rcp_f32_e32 v64, v64
	v_rcp_f32_e32 v65, v65
	s_nop 0
	v_cvt_pk_bf16_f32 v65, v64, v65
	v_pk_mul_f32 v[62:63], v[62:63], v[242:243]
	v_exp_f32_e32 v62, v62
	v_exp_f32_e32 v63, v63
	s_nop 0
	v_pk_add_f32 v[62:63], v[62:63], v[244:245]
	v_rcp_f32_e32 v62, v62
	v_rcp_f32_e32 v63, v63
	s_nop 0
	v_cvt_pk_bf16_f32 v64, v62, v63
	v_pk_mul_f32 v[60:61], v[60:61], v[242:243]
	v_exp_f32_e32 v60, v60
	v_exp_f32_e32 v61, v61
	s_nop 0
	v_pk_add_f32 v[60:61], v[60:61], v[244:245]
	v_rcp_f32_e32 v60, v60
	v_rcp_f32_e32 v61, v61
	s_nop 0
	v_cvt_pk_bf16_f32 v63, v60, v61
	v_pk_mul_f32 v[58:59], v[58:59], v[242:243]
	v_exp_f32_e32 v58, v58
	v_exp_f32_e32 v59, v59
	s_nop 0
	v_pk_add_f32 v[58:59], v[58:59], v[244:245]
	v_rcp_f32_e32 v58, v58
	v_rcp_f32_e32 v59, v59
	s_nop 0
	v_cvt_pk_bf16_f32 v62, v58, v59
	global_store_dwordx4 v[92:93], v[62:65], off
	v_pk_mul_f32 v[56:57], v[56:57], v[242:243]
	v_exp_f32_e32 v56, v56
	v_exp_f32_e32 v57, v57
	s_nop 0
	v_pk_add_f32 v[56:57], v[56:57], v[244:245]
	v_rcp_f32_e32 v56, v56
	v_rcp_f32_e32 v57, v57
	s_nop 0
	v_cvt_pk_bf16_f32 v57, v56, v57
	v_pk_mul_f32 v[54:55], v[54:55], v[242:243]
	v_exp_f32_e32 v54, v54
	v_exp_f32_e32 v55, v55
	s_nop 0
	v_pk_add_f32 v[54:55], v[54:55], v[244:245]
	v_rcp_f32_e32 v54, v54
	v_rcp_f32_e32 v55, v55
	s_nop 0
	v_cvt_pk_bf16_f32 v56, v54, v55
	v_pk_mul_f32 v[52:53], v[52:53], v[242:243]
	v_exp_f32_e32 v52, v52
	v_exp_f32_e32 v53, v53
	s_nop 0
	v_pk_add_f32 v[52:53], v[52:53], v[244:245]
	v_rcp_f32_e32 v52, v52
	v_rcp_f32_e32 v53, v53
	s_nop 0
	v_cvt_pk_bf16_f32 v55, v52, v53
	v_pk_mul_f32 v[50:51], v[50:51], v[242:243]
	v_exp_f32_e32 v50, v50
	v_exp_f32_e32 v51, v51
	s_nop 0
	v_pk_add_f32 v[50:51], v[50:51], v[244:245]
	v_rcp_f32_e32 v50, v50
	v_rcp_f32_e32 v51, v51
	s_nop 0
	v_cvt_pk_bf16_f32 v54, v50, v51
	global_store_dwordx4 v[92:93], v[54:57], off offset:1024
	v_pk_mul_f32 v[48:49], v[48:49], v[242:243]
	v_exp_f32_e32 v48, v48
	v_exp_f32_e32 v49, v49
	s_nop 0
	v_pk_add_f32 v[48:49], v[48:49], v[244:245]
	v_rcp_f32_e32 v48, v48
	v_rcp_f32_e32 v49, v49
	s_nop 0
	v_cvt_pk_bf16_f32 v49, v48, v49
	v_pk_mul_f32 v[46:47], v[46:47], v[242:243]
	v_exp_f32_e32 v46, v46
	v_exp_f32_e32 v47, v47
	s_nop 0
	v_pk_add_f32 v[46:47], v[46:47], v[244:245]
	v_rcp_f32_e32 v46, v46
	v_rcp_f32_e32 v47, v47
	s_nop 0
	v_cvt_pk_bf16_f32 v48, v46, v47
	v_pk_mul_f32 v[44:45], v[44:45], v[242:243]
	v_exp_f32_e32 v44, v44
	v_exp_f32_e32 v45, v45
	s_nop 0
	v_pk_add_f32 v[44:45], v[44:45], v[244:245]
	v_rcp_f32_e32 v44, v44
	v_rcp_f32_e32 v45, v45
	s_nop 0
	v_cvt_pk_bf16_f32 v47, v44, v45
	v_pk_mul_f32 v[42:43], v[42:43], v[242:243]
	v_exp_f32_e32 v42, v42
	v_exp_f32_e32 v43, v43
	s_nop 0
	v_pk_add_f32 v[42:43], v[42:43], v[244:245]
	v_rcp_f32_e32 v42, v42
	v_rcp_f32_e32 v43, v43
	s_nop 0
	v_cvt_pk_bf16_f32 v46, v42, v43
	global_store_dwordx4 v[92:93], v[46:49], off offset:2048
	v_pk_mul_f32 v[40:41], v[40:41], v[242:243]
	v_exp_f32_e32 v40, v40
	v_exp_f32_e32 v41, v41
	s_nop 0
	v_pk_add_f32 v[40:41], v[40:41], v[244:245]
	v_rcp_f32_e32 v40, v40
	v_rcp_f32_e32 v41, v41
	s_nop 0
	v_cvt_pk_bf16_f32 v41, v40, v41
	v_pk_mul_f32 v[38:39], v[38:39], v[242:243]
	v_exp_f32_e32 v38, v38
	v_exp_f32_e32 v39, v39
	s_nop 0
	v_pk_add_f32 v[38:39], v[38:39], v[244:245]
	v_rcp_f32_e32 v38, v38
	v_rcp_f32_e32 v39, v39
	s_nop 0
	v_cvt_pk_bf16_f32 v40, v38, v39
	v_pk_mul_f32 v[36:37], v[36:37], v[242:243]
	v_exp_f32_e32 v36, v36
	v_exp_f32_e32 v37, v37
	s_nop 0
	v_pk_add_f32 v[36:37], v[36:37], v[244:245]
	v_rcp_f32_e32 v36, v36
	v_rcp_f32_e32 v37, v37
	s_nop 0
	v_cvt_pk_bf16_f32 v39, v36, v37
	v_pk_mul_f32 v[34:35], v[34:35], v[242:243]
	v_exp_f32_e32 v34, v34
	v_exp_f32_e32 v35, v35
	s_nop 0
	v_pk_add_f32 v[34:35], v[34:35], v[244:245]
	v_rcp_f32_e32 v34, v34
	v_rcp_f32_e32 v35, v35
	s_nop 0
	v_cvt_pk_bf16_f32 v38, v34, v35
	global_store_dwordx4 v[92:93], v[38:41], off offset:3072
	v_pk_mul_f32 v[28:29], v[28:29], v[242:243]
	v_exp_f32_e32 v28, v28
	v_exp_f32_e32 v29, v29
	s_nop 0
	v_pk_add_f32 v[28:29], v[28:29], v[244:245]
	v_rcp_f32_e32 v28, v28
	v_rcp_f32_e32 v29, v29
	s_nop 0
	v_cvt_pk_bf16_f32 v31, v28, v29
	v_addc_co_u32_e32 v27, vcc, 0, v157, vcc
	global_store_dwordx4 v[26:27], v[30:33], off
	v_pk_mul_f32 v[24:25], v[24:25], v[242:243]
	v_exp_f32_e32 v24, v24
	v_exp_f32_e32 v25, v25
	s_nop 0
	v_pk_add_f32 v[24:25], v[24:25], v[244:245]
	v_rcp_f32_e32 v24, v24
	v_rcp_f32_e32 v25, v25
	s_nop 0
	v_cvt_pk_bf16_f32 v25, v24, v25
	v_pk_mul_f32 v[22:23], v[22:23], v[242:243]
	v_exp_f32_e32 v22, v22
	v_exp_f32_e32 v23, v23
	s_nop 0
	v_pk_add_f32 v[22:23], v[22:23], v[244:245]
	v_rcp_f32_e32 v22, v22
	v_rcp_f32_e32 v23, v23
	s_nop 0
	v_cvt_pk_bf16_f32 v24, v22, v23
	v_pk_mul_f32 v[20:21], v[20:21], v[242:243]
	v_exp_f32_e32 v20, v20
	v_exp_f32_e32 v21, v21
	s_nop 0
	v_pk_add_f32 v[20:21], v[20:21], v[244:245]
	v_rcp_f32_e32 v20, v20
	v_rcp_f32_e32 v21, v21
	s_nop 0
	v_cvt_pk_bf16_f32 v23, v20, v21
	v_pk_mul_f32 v[18:19], v[18:19], v[242:243]
	v_exp_f32_e32 v18, v18
	v_exp_f32_e32 v19, v19
	s_nop 0
	v_pk_add_f32 v[18:19], v[18:19], v[244:245]
	v_rcp_f32_e32 v18, v18
	v_rcp_f32_e32 v19, v19
	s_nop 0
	v_cvt_pk_bf16_f32 v22, v18, v19
	global_store_dwordx4 v[26:27], v[22:25], off offset:1024
	v_pk_mul_f32 v[16:17], v[16:17], v[242:243]
	v_exp_f32_e32 v16, v16
	v_exp_f32_e32 v17, v17
	s_nop 0
	v_pk_add_f32 v[16:17], v[16:17], v[244:245]
	v_rcp_f32_e32 v16, v16
	v_rcp_f32_e32 v17, v17
	s_nop 0
	v_cvt_pk_bf16_f32 v17, v16, v17
	v_pk_mul_f32 v[14:15], v[14:15], v[242:243]
	v_exp_f32_e32 v14, v14
	v_exp_f32_e32 v15, v15
	s_nop 0
	v_pk_add_f32 v[14:15], v[14:15], v[244:245]
	v_rcp_f32_e32 v14, v14
	v_rcp_f32_e32 v15, v15
	s_nop 0
	v_cvt_pk_bf16_f32 v16, v14, v15
	v_pk_mul_f32 v[12:13], v[12:13], v[242:243]
	v_exp_f32_e32 v12, v12
	v_exp_f32_e32 v13, v13
	s_nop 0
	v_pk_add_f32 v[12:13], v[12:13], v[244:245]
	v_rcp_f32_e32 v12, v12
	v_rcp_f32_e32 v13, v13
	s_nop 0
	v_cvt_pk_bf16_f32 v15, v12, v13
	v_pk_mul_f32 v[10:11], v[10:11], v[242:243]
	v_exp_f32_e32 v10, v10
	v_exp_f32_e32 v11, v11
	s_nop 0
	v_pk_add_f32 v[10:11], v[10:11], v[244:245]
	v_rcp_f32_e32 v10, v10
	v_rcp_f32_e32 v11, v11
	s_nop 0
	v_cvt_pk_bf16_f32 v14, v10, v11
	global_store_dwordx4 v[26:27], v[14:17], off offset:2048
	v_pk_mul_f32 v[4:5], v[4:5], v[242:243]
	v_exp_f32_e32 v4, v4
	v_exp_f32_e32 v5, v5
	s_nop 0
	v_pk_add_f32 v[4:5], v[4:5], v[244:245]
	v_rcp_f32_e32 v4, v4
	v_rcp_f32_e32 v5, v5
	s_nop 0
	v_cvt_pk_bf16_f32 v5, v4, v5
	v_pk_mul_f32 v[2:3], v[2:3], v[242:243]
	v_exp_f32_e32 v2, v2
	v_exp_f32_e32 v3, v3
	s_nop 0
	v_pk_add_f32 v[2:3], v[2:3], v[244:245]
	v_rcp_f32_e32 v2, v2
	v_rcp_f32_e32 v3, v3
	s_nop 0
	v_cvt_pk_bf16_f32 v4, v2, v3
	v_pk_mul_f32 v[8:9], v[8:9], v[242:243]
	v_exp_f32_e32 v8, v8
	v_exp_f32_e32 v9, v9
	s_nop 0
	v_pk_add_f32 v[8:9], v[8:9], v[244:245]
	v_rcp_f32_e32 v8, v8
	v_rcp_f32_e32 v9, v9
	s_nop 0
	v_cvt_pk_bf16_f32 v3, v8, v9
	v_pk_mul_f32 v[6:7], v[6:7], v[242:243]
	v_exp_f32_e32 v6, v6
	v_exp_f32_e32 v7, v7
	s_nop 0
	v_pk_add_f32 v[6:7], v[6:7], v[244:245]
	v_rcp_f32_e32 v6, v6
	v_rcp_f32_e32 v7, v7
	s_nop 0
	v_cvt_pk_bf16_f32 v2, v6, v7
	global_store_dwordx4 v[26:27], v[2:5], off offset:3072
	s_mov_b32 s100, 1
	s_branch .LBB0_234
